# K=2816 sample-row skinny GEMMs (P2, P17): straight-line K loop with a 4-deep ring of operand sets (48 loads in flight) instead of double buffering
# speedup vs baseline: 1.0029x; 1.0029x over previous
; template <bool PAIR, class F>
; __device__ __forceinline__ void skinny(const bf16_t* A, int lda, const bf16_t* Bt, int ldb, int K, int tile_lo, int tile_hi, int kmode, int bx, int G, int tid_, LAS unsigned char* lds, F f) {
;     ...
;         const int rbp = un & 3, cgrp = un >> 2, tile = tile_lo + cgrp / GPT, cgp = (cgrp % GPT) * 4 + cgl;
;         const int n0 = tile * 256 + cgp * 16, row0 = MP + rbp * 32 + fr;
;         const bf16_t* ap = A + (size_t)row0 * lda + (kmode ? 256 * (tile >> 1) : 0) + fq * 8;
;         const bf16_t* bp = Bt + (size_t)(n0 + fr) * ldb + fq * 8;
;         f32x4 a00 = (f32x4){0.f, 0.f, 0.f, 0.f}, a01 = a00, a10 = a00, a11 = a00;
;         for (int k0 = kbeg; k0 < kbeg + Kh; k0 += 128) {
; #pragma unroll
;             for (int kk = 0; kk < 128; kk += 32) {
;                 const bf16x8 x0 = *(const bf16x8*)(ap + k0 + kk), x1 = *(const bf16x8*)(ap + (size_t)16 * lda + k0 + kk), b = *(const bf16x8*)(bp + k0 + kk);
;                 a00 = __builtin_amdgcn_mfma_f32_16x16x32_bf16(b, x0, a00, 0, 0, 0); a01 = __builtin_amdgcn_mfma_f32_16x16x32_bf16(b, x1, a01, 0, 0, 0);
;                 if (PAIR) { const bf16x8 b2 = *(const bf16x8*)(bp + (size_t)128 * ldb + k0 + kk);
;                     a10 = __builtin_amdgcn_mfma_f32_16x16x32_bf16(b2, x0, a10, 0, 0, 0); a11 = __builtin_amdgcn_mfma_f32_16x16x32_bf16(b2, x1, a11, 0, 0, 0); }
;             }
.LBB0_427:
	s_ashr_i32 s20, s24, 2
	s_lshr_b32 s21, s20, 30
	s_add_i32 s25, s20, s21
	s_and_b32 s21, s25, 0x3fffffc
	s_sub_i32 s20, s20, s21
	s_lshl_b32 s20, s20, 6
	s_or_b32 s21, s20, s13
	s_lshl_b32 s20, s24, 5
	s_and_b32 s20, s20, 0x60
	v_or_b32_e32 v22, s20, v18
	s_lshl_b32 s20, s25, 6
	s_and_b32 s20, s20, 0xffffff00
	v_or_b32_e32 v23, 0x4000, v22
	s_add_i32 s25, s21, s20
	v_mul_u32_u24_e32 v0, 0xb00, v23
	v_or_b32_e32 v1, s25, v18
	v_lshlrev_b32_e32 v8, 1, v0
	v_mad_i64_i32 v[14:15], s[26:27], v1, s23, v[12:13]
	v_mov_b64_e32 v[16:17], v[10:11]
	s_mov_b32 s25, s22
	v_mov_b32_e32 v4, v9
	v_mov_b32_e32 v5, v9
	v_mov_b32_e32 v6, v9
	v_mov_b32_e32 v7, v9
	v_mov_b32_e32 v0, v9
	v_mov_b32_e32 v1, v9
	v_mov_b32_e32 v2, v9
	v_mov_b32_e32 v3, v9
	v_lshl_add_u64 v[126:127], v[16:17], 0, v[8:9]
	v_lshl_add_u64 v[124:125], v[16:17], 0, v[14:15]
	v_add_co_u32_e32 v52, vcc, 0x9e00000, v126
	s_nop 1
	v_addc_co_u32_e32 v53, vcc, 0, v127, vcc
	v_add_co_u32_e32 v54, vcc, 0x9e16000, v126
	s_nop 1
	v_addc_co_u32_e32 v55, vcc, 0, v127, vcc
	v_lshl_add_u64 v[16:17], v[16:17], 0, s[8:9]
	global_load_dwordx4 v[24:27], v[124:125], off offset:-128
	global_load_dwordx4 v[28:31], v[124:125], off offset:-64
	global_load_dwordx4 v[32:35], v[124:125], off
	global_load_dwordx4 v[36:39], v[124:125], off offset:64
	global_load_dwordx4 v[40:43], v[52:53], off
	global_load_dwordx4 v[48:51], v[54:55], off
	global_load_dwordx4 v[44:47], v[52:53], off offset:64
	global_load_dwordx4 v[64:67], v[54:55], off offset:64
	global_load_dwordx4 v[56:59], v[52:53], off offset:128
	global_load_dwordx4 v[68:71], v[54:55], off offset:128
	global_load_dwordx4 v[60:63], v[52:53], off offset:192
	global_load_dwordx4 v[72:75], v[54:55], off offset:192
	v_lshl_add_u64 v[126:127], v[16:17], 0, v[8:9]
	v_lshl_add_u64 v[124:125], v[16:17], 0, v[14:15]
	v_add_co_u32_e32 v52, vcc, 0x9e00000, v126
	s_nop 1
	v_addc_co_u32_e32 v53, vcc, 0, v127, vcc
	v_add_co_u32_e32 v54, vcc, 0x9e16000, v126
	s_nop 1
	v_addc_co_u32_e32 v55, vcc, 0, v127, vcc
	v_lshl_add_u64 v[16:17], v[16:17], 0, s[8:9]
	global_load_dwordx4 v[76:79], v[124:125], off offset:-128
	global_load_dwordx4 v[80:83], v[124:125], off offset:-64
	global_load_dwordx4 v[84:87], v[124:125], off
	global_load_dwordx4 v[88:91], v[124:125], off offset:64
	global_load_dwordx4 v[92:95], v[52:53], off
	global_load_dwordx4 v[108:111], v[54:55], off
	global_load_dwordx4 v[96:99], v[52:53], off offset:64
	global_load_dwordx4 v[112:115], v[54:55], off offset:64
	global_load_dwordx4 v[100:103], v[52:53], off offset:128
	global_load_dwordx4 v[116:119], v[54:55], off offset:128
	global_load_dwordx4 v[104:107], v[52:53], off offset:192
	global_load_dwordx4 v[120:123], v[54:55], off offset:192
	v_lshl_add_u64 v[126:127], v[16:17], 0, v[8:9]
	v_lshl_add_u64 v[124:125], v[16:17], 0, v[14:15]
	v_add_co_u32_e32 v52, vcc, 0x9e00000, v126
	s_nop 1
	v_addc_co_u32_e32 v53, vcc, 0, v127, vcc
	v_add_co_u32_e32 v54, vcc, 0x9e16000, v126
	s_nop 1
	v_addc_co_u32_e32 v55, vcc, 0, v127, vcc
	v_lshl_add_u64 v[16:17], v[16:17], 0, s[8:9]
	global_load_dwordx4 v[128:131], v[124:125], off offset:-128
	global_load_dwordx4 v[132:135], v[124:125], off offset:-64
	global_load_dwordx4 v[136:139], v[124:125], off
	global_load_dwordx4 v[140:143], v[124:125], off offset:64
	global_load_dwordx4 v[144:147], v[52:53], off
	global_load_dwordx4 v[160:163], v[54:55], off
	global_load_dwordx4 v[148:151], v[52:53], off offset:64
	global_load_dwordx4 v[164:167], v[54:55], off offset:64
	global_load_dwordx4 v[152:155], v[52:53], off offset:128
	global_load_dwordx4 v[168:171], v[54:55], off offset:128
	global_load_dwordx4 v[156:159], v[52:53], off offset:192
	global_load_dwordx4 v[172:175], v[54:55], off offset:192
	v_lshl_add_u64 v[126:127], v[16:17], 0, v[8:9]
	v_lshl_add_u64 v[124:125], v[16:17], 0, v[14:15]
	v_add_co_u32_e32 v52, vcc, 0x9e00000, v126
	s_nop 1
	v_addc_co_u32_e32 v53, vcc, 0, v127, vcc
	v_add_co_u32_e32 v54, vcc, 0x9e16000, v126
	s_nop 1
	v_addc_co_u32_e32 v55, vcc, 0, v127, vcc
	v_lshl_add_u64 v[16:17], v[16:17], 0, s[8:9]
	global_load_dwordx4 v[176:179], v[124:125], off offset:-128
	global_load_dwordx4 v[180:183], v[124:125], off offset:-64
	global_load_dwordx4 v[184:187], v[124:125], off
	global_load_dwordx4 v[192:195], v[124:125], off offset:64
	global_load_dwordx4 v[196:199], v[52:53], off
	global_load_dwordx4 v[216:219], v[54:55], off
	global_load_dwordx4 v[204:207], v[52:53], off offset:64
	global_load_dwordx4 v[220:223], v[54:55], off offset:64
	global_load_dwordx4 v[208:211], v[52:53], off offset:128
	global_load_dwordx4 v[224:227], v[54:55], off offset:128
	global_load_dwordx4 v[212:215], v[52:53], off offset:192
	global_load_dwordx4 v[232:235], v[54:55], off offset:192
	s_waitcnt vmcnt(36)
	v_mfma_f32_16x16x32_bf16 v[4:7], v[24:27], v[40:43], v[4:7]
	v_mfma_f32_16x16x32_bf16 v[0:3], v[24:27], v[48:51], v[0:3]
	v_mfma_f32_16x16x32_bf16 v[4:7], v[28:31], v[44:47], v[4:7]
	v_mfma_f32_16x16x32_bf16 v[0:3], v[28:31], v[64:67], v[0:3]
	v_mfma_f32_16x16x32_bf16 v[4:7], v[32:35], v[56:59], v[4:7]
	v_mfma_f32_16x16x32_bf16 v[0:3], v[32:35], v[68:71], v[0:3]
	v_mfma_f32_16x16x32_bf16 v[4:7], v[36:39], v[60:63], v[4:7]
	v_mfma_f32_16x16x32_bf16 v[0:3], v[36:39], v[72:75], v[0:3]
	v_lshl_add_u64 v[126:127], v[16:17], 0, v[8:9]
	v_lshl_add_u64 v[124:125], v[16:17], 0, v[14:15]
	v_add_co_u32_e32 v52, vcc, 0x9e00000, v126
	s_nop 1
	v_addc_co_u32_e32 v53, vcc, 0, v127, vcc
	v_add_co_u32_e32 v54, vcc, 0x9e16000, v126
	s_nop 1
	v_addc_co_u32_e32 v55, vcc, 0, v127, vcc
	v_lshl_add_u64 v[16:17], v[16:17], 0, s[8:9]
	global_load_dwordx4 v[24:27], v[124:125], off offset:-128
	global_load_dwordx4 v[28:31], v[124:125], off offset:-64
	global_load_dwordx4 v[32:35], v[124:125], off
	global_load_dwordx4 v[36:39], v[124:125], off offset:64
	global_load_dwordx4 v[40:43], v[52:53], off
	global_load_dwordx4 v[48:51], v[54:55], off
	global_load_dwordx4 v[44:47], v[52:53], off offset:64
	global_load_dwordx4 v[64:67], v[54:55], off offset:64
	global_load_dwordx4 v[56:59], v[52:53], off offset:128
	global_load_dwordx4 v[68:71], v[54:55], off offset:128
	global_load_dwordx4 v[60:63], v[52:53], off offset:192
	global_load_dwordx4 v[72:75], v[54:55], off offset:192
	s_waitcnt vmcnt(36)
; template <bool PAIR, class F>
; __device__ __forceinline__ void skinny(const bf16_t* A, int lda, const bf16_t* Bt, int ldb, int K, int tile_lo, int tile_hi, int kmode, int bx, int G, int tid_, LAS unsigned char* lds, F f) {
;     ...
;         for (int k0 = kbeg; k0 < kbeg + Kh; k0 += 128) {
; #pragma unroll
;             for (int kk = 0; kk < 128; kk += 32) {
;                 const bf16x8 x0 = *(const bf16x8*)(ap + k0 + kk), x1 = *(const bf16x8*)(ap + (size_t)16 * lda + k0 + kk), b = *(const bf16x8*)(bp + k0 + kk);
;                 a00 = __builtin_amdgcn_mfma_f32_16x16x32_bf16(b, x0, a00, 0, 0, 0); a01 = __builtin_amdgcn_mfma_f32_16x16x32_bf16(b, x1, a01, 0, 0, 0);
;                 if (PAIR) { const bf16x8 b2 = *(const bf16x8*)(bp + (size_t)128 * ldb + k0 + kk);
;                     a10 = __builtin_amdgcn_mfma_f32_16x16x32_bf16(b2, x0, a10, 0, 0, 0); a11 = __builtin_amdgcn_mfma_f32_16x16x32_bf16(b2, x1, a11, 0, 0, 0); }
;             }
	v_mfma_f32_16x16x32_bf16 v[4:7], v[76:79], v[92:95], v[4:7]
	v_mfma_f32_16x16x32_bf16 v[0:3], v[76:79], v[108:111], v[0:3]
	v_mfma_f32_16x16x32_bf16 v[4:7], v[80:83], v[96:99], v[4:7]
	v_mfma_f32_16x16x32_bf16 v[0:3], v[80:83], v[112:115], v[0:3]
	v_mfma_f32_16x16x32_bf16 v[4:7], v[84:87], v[100:103], v[4:7]
	v_mfma_f32_16x16x32_bf16 v[0:3], v[84:87], v[116:119], v[0:3]
	v_mfma_f32_16x16x32_bf16 v[4:7], v[88:91], v[104:107], v[4:7]
	v_mfma_f32_16x16x32_bf16 v[0:3], v[88:91], v[120:123], v[0:3]
	v_lshl_add_u64 v[126:127], v[16:17], 0, v[8:9]
	v_lshl_add_u64 v[124:125], v[16:17], 0, v[14:15]
	v_add_co_u32_e32 v52, vcc, 0x9e00000, v126
	s_nop 1
	v_addc_co_u32_e32 v53, vcc, 0, v127, vcc
	v_add_co_u32_e32 v54, vcc, 0x9e16000, v126
	s_nop 1
	v_addc_co_u32_e32 v55, vcc, 0, v127, vcc
	v_lshl_add_u64 v[16:17], v[16:17], 0, s[8:9]
	global_load_dwordx4 v[76:79], v[124:125], off offset:-128
	global_load_dwordx4 v[80:83], v[124:125], off offset:-64
	global_load_dwordx4 v[84:87], v[124:125], off
	global_load_dwordx4 v[88:91], v[124:125], off offset:64
	global_load_dwordx4 v[92:95], v[52:53], off
	global_load_dwordx4 v[108:111], v[54:55], off
	global_load_dwordx4 v[96:99], v[52:53], off offset:64
	global_load_dwordx4 v[112:115], v[54:55], off offset:64
	global_load_dwordx4 v[100:103], v[52:53], off offset:128
	global_load_dwordx4 v[116:119], v[54:55], off offset:128
	global_load_dwordx4 v[104:107], v[52:53], off offset:192
	global_load_dwordx4 v[120:123], v[54:55], off offset:192
	s_waitcnt vmcnt(36)
	v_mfma_f32_16x16x32_bf16 v[4:7], v[128:131], v[144:147], v[4:7]
	v_mfma_f32_16x16x32_bf16 v[0:3], v[128:131], v[160:163], v[0:3]
	v_mfma_f32_16x16x32_bf16 v[4:7], v[132:135], v[148:151], v[4:7]
	v_mfma_f32_16x16x32_bf16 v[0:3], v[132:135], v[164:167], v[0:3]
	v_mfma_f32_16x16x32_bf16 v[4:7], v[136:139], v[152:155], v[4:7]
	v_mfma_f32_16x16x32_bf16 v[0:3], v[136:139], v[168:171], v[0:3]
	v_mfma_f32_16x16x32_bf16 v[4:7], v[140:143], v[156:159], v[4:7]
	v_mfma_f32_16x16x32_bf16 v[0:3], v[140:143], v[172:175], v[0:3]
	v_lshl_add_u64 v[126:127], v[16:17], 0, v[8:9]
	v_lshl_add_u64 v[124:125], v[16:17], 0, v[14:15]
	v_add_co_u32_e32 v52, vcc, 0x9e00000, v126
	s_nop 1
	v_addc_co_u32_e32 v53, vcc, 0, v127, vcc
	v_add_co_u32_e32 v54, vcc, 0x9e16000, v126
	s_nop 1
	v_addc_co_u32_e32 v55, vcc, 0, v127, vcc
	v_lshl_add_u64 v[16:17], v[16:17], 0, s[8:9]
	global_load_dwordx4 v[128:131], v[124:125], off offset:-128
	global_load_dwordx4 v[132:135], v[124:125], off offset:-64
	global_load_dwordx4 v[136:139], v[124:125], off
	global_load_dwordx4 v[140:143], v[124:125], off offset:64
	global_load_dwordx4 v[144:147], v[52:53], off
	global_load_dwordx4 v[160:163], v[54:55], off
	global_load_dwordx4 v[148:151], v[52:53], off offset:64
	global_load_dwordx4 v[164:167], v[54:55], off offset:64
	global_load_dwordx4 v[152:155], v[52:53], off offset:128
	global_load_dwordx4 v[168:171], v[54:55], off offset:128
	global_load_dwordx4 v[156:159], v[52:53], off offset:192
	global_load_dwordx4 v[172:175], v[54:55], off offset:192
	s_waitcnt vmcnt(36)
	v_mfma_f32_16x16x32_bf16 v[4:7], v[176:179], v[196:199], v[4:7]
	v_mfma_f32_16x16x32_bf16 v[0:3], v[176:179], v[216:219], v[0:3]
	v_mfma_f32_16x16x32_bf16 v[4:7], v[180:183], v[204:207], v[4:7]
	v_mfma_f32_16x16x32_bf16 v[0:3], v[180:183], v[220:223], v[0:3]
	v_mfma_f32_16x16x32_bf16 v[4:7], v[184:187], v[208:211], v[4:7]
	v_mfma_f32_16x16x32_bf16 v[0:3], v[184:187], v[224:227], v[0:3]
	v_mfma_f32_16x16x32_bf16 v[4:7], v[192:195], v[212:215], v[4:7]
	v_mfma_f32_16x16x32_bf16 v[0:3], v[192:195], v[232:235], v[0:3]
	v_lshl_add_u64 v[126:127], v[16:17], 0, v[8:9]
	v_lshl_add_u64 v[124:125], v[16:17], 0, v[14:15]
	v_add_co_u32_e32 v52, vcc, 0x9e00000, v126
	s_nop 1
	v_addc_co_u32_e32 v53, vcc, 0, v127, vcc
	v_add_co_u32_e32 v54, vcc, 0x9e16000, v126
	s_nop 1
	v_addc_co_u32_e32 v55, vcc, 0, v127, vcc
	v_lshl_add_u64 v[16:17], v[16:17], 0, s[8:9]
	global_load_dwordx4 v[176:179], v[124:125], off offset:-128
	global_load_dwordx4 v[180:183], v[124:125], off offset:-64
	global_load_dwordx4 v[184:187], v[124:125], off
	global_load_dwordx4 v[192:195], v[124:125], off offset:64
	global_load_dwordx4 v[196:199], v[52:53], off
	global_load_dwordx4 v[216:219], v[54:55], off
	global_load_dwordx4 v[204:207], v[52:53], off offset:64
	global_load_dwordx4 v[220:223], v[54:55], off offset:64
	global_load_dwordx4 v[208:211], v[52:53], off offset:128
	global_load_dwordx4 v[224:227], v[54:55], off offset:128
	global_load_dwordx4 v[212:215], v[52:53], off offset:192
	global_load_dwordx4 v[232:235], v[54:55], off offset:192
	s_waitcnt vmcnt(36)
	v_mfma_f32_16x16x32_bf16 v[4:7], v[24:27], v[40:43], v[4:7]
	v_mfma_f32_16x16x32_bf16 v[0:3], v[24:27], v[48:51], v[0:3]
	v_mfma_f32_16x16x32_bf16 v[4:7], v[28:31], v[44:47], v[4:7]
	v_mfma_f32_16x16x32_bf16 v[0:3], v[28:31], v[64:67], v[0:3]
	v_mfma_f32_16x16x32_bf16 v[4:7], v[32:35], v[56:59], v[4:7]
	v_mfma_f32_16x16x32_bf16 v[0:3], v[32:35], v[68:71], v[0:3]
	v_mfma_f32_16x16x32_bf16 v[4:7], v[36:39], v[60:63], v[4:7]
	v_mfma_f32_16x16x32_bf16 v[0:3], v[36:39], v[72:75], v[0:3]
	v_lshl_add_u64 v[126:127], v[16:17], 0, v[8:9]
	v_lshl_add_u64 v[124:125], v[16:17], 0, v[14:15]
	v_add_co_u32_e32 v52, vcc, 0x9e00000, v126
	s_nop 1
	v_addc_co_u32_e32 v53, vcc, 0, v127, vcc
	v_add_co_u32_e32 v54, vcc, 0x9e16000, v126
	s_nop 1
	v_addc_co_u32_e32 v55, vcc, 0, v127, vcc
	v_lshl_add_u64 v[16:17], v[16:17], 0, s[8:9]
	global_load_dwordx4 v[24:27], v[124:125], off offset:-128
	global_load_dwordx4 v[28:31], v[124:125], off offset:-64
	global_load_dwordx4 v[32:35], v[124:125], off
	global_load_dwordx4 v[36:39], v[124:125], off offset:64
	global_load_dwordx4 v[40:43], v[52:53], off
	global_load_dwordx4 v[48:51], v[54:55], off
	global_load_dwordx4 v[44:47], v[52:53], off offset:64
	global_load_dwordx4 v[64:67], v[54:55], off offset:64
	global_load_dwordx4 v[56:59], v[52:53], off offset:128
	global_load_dwordx4 v[68:71], v[54:55], off offset:128
	global_load_dwordx4 v[60:63], v[52:53], off offset:192
	global_load_dwordx4 v[72:75], v[54:55], off offset:192
	s_waitcnt vmcnt(36)
; template <bool PAIR, class F>
; __device__ __forceinline__ void skinny(const bf16_t* A, int lda, const bf16_t* Bt, int ldb, int K, int tile_lo, int tile_hi, int kmode, int bx, int G, int tid_, LAS unsigned char* lds, F f) {
;     ...
;         for (int k0 = kbeg; k0 < kbeg + Kh; k0 += 128) {
; #pragma unroll
;             for (int kk = 0; kk < 128; kk += 32) {
;                 const bf16x8 x0 = *(const bf16x8*)(ap + k0 + kk), x1 = *(const bf16x8*)(ap + (size_t)16 * lda + k0 + kk), b = *(const bf16x8*)(bp + k0 + kk);
;                 a00 = __builtin_amdgcn_mfma_f32_16x16x32_bf16(b, x0, a00, 0, 0, 0); a01 = __builtin_amdgcn_mfma_f32_16x16x32_bf16(b, x1, a01, 0, 0, 0);
;                 if (PAIR) { const bf16x8 b2 = *(const bf16x8*)(bp + (size_t)128 * ldb + k0 + kk);
;                     a10 = __builtin_amdgcn_mfma_f32_16x16x32_bf16(b2, x0, a10, 0, 0, 0); a11 = __builtin_amdgcn_mfma_f32_16x16x32_bf16(b2, x1, a11, 0, 0, 0); }
;             }
;         }
;         if (kh == 1) { X[0] = a00; X[1] = a01; if (PAIR) { X[2] = a10; X[3] = a11; } }
	v_mfma_f32_16x16x32_bf16 v[4:7], v[76:79], v[92:95], v[4:7]
	v_mfma_f32_16x16x32_bf16 v[0:3], v[76:79], v[108:111], v[0:3]
	v_mfma_f32_16x16x32_bf16 v[4:7], v[80:83], v[96:99], v[4:7]
	v_mfma_f32_16x16x32_bf16 v[0:3], v[80:83], v[112:115], v[0:3]
	v_mfma_f32_16x16x32_bf16 v[4:7], v[84:87], v[100:103], v[4:7]
	v_mfma_f32_16x16x32_bf16 v[0:3], v[84:87], v[116:119], v[0:3]
	v_mfma_f32_16x16x32_bf16 v[4:7], v[88:91], v[104:107], v[4:7]
	v_mfma_f32_16x16x32_bf16 v[0:3], v[88:91], v[120:123], v[0:3]
	v_lshl_add_u64 v[126:127], v[16:17], 0, v[8:9]
	v_lshl_add_u64 v[124:125], v[16:17], 0, v[14:15]
	v_add_co_u32_e32 v52, vcc, 0x9e00000, v126
	s_nop 1
	v_addc_co_u32_e32 v53, vcc, 0, v127, vcc
	v_add_co_u32_e32 v54, vcc, 0x9e16000, v126
	s_nop 1
	v_addc_co_u32_e32 v55, vcc, 0, v127, vcc
	v_lshl_add_u64 v[16:17], v[16:17], 0, s[8:9]
	global_load_dwordx4 v[76:79], v[124:125], off offset:-128
	global_load_dwordx4 v[80:83], v[124:125], off offset:-64
	global_load_dwordx4 v[84:87], v[124:125], off
	global_load_dwordx4 v[88:91], v[124:125], off offset:64
	global_load_dwordx4 v[92:95], v[52:53], off
	global_load_dwordx4 v[108:111], v[54:55], off
	global_load_dwordx4 v[96:99], v[52:53], off offset:64
	global_load_dwordx4 v[112:115], v[54:55], off offset:64
	global_load_dwordx4 v[100:103], v[52:53], off offset:128
	global_load_dwordx4 v[116:119], v[54:55], off offset:128
	global_load_dwordx4 v[104:107], v[52:53], off offset:192
	global_load_dwordx4 v[120:123], v[54:55], off offset:192
	s_waitcnt vmcnt(36)
	v_mfma_f32_16x16x32_bf16 v[4:7], v[128:131], v[144:147], v[4:7]
	v_mfma_f32_16x16x32_bf16 v[0:3], v[128:131], v[160:163], v[0:3]
	v_mfma_f32_16x16x32_bf16 v[4:7], v[132:135], v[148:151], v[4:7]
	v_mfma_f32_16x16x32_bf16 v[0:3], v[132:135], v[164:167], v[0:3]
	v_mfma_f32_16x16x32_bf16 v[4:7], v[136:139], v[152:155], v[4:7]
	v_mfma_f32_16x16x32_bf16 v[0:3], v[136:139], v[168:171], v[0:3]
	v_mfma_f32_16x16x32_bf16 v[4:7], v[140:143], v[156:159], v[4:7]
	v_mfma_f32_16x16x32_bf16 v[0:3], v[140:143], v[172:175], v[0:3]
	v_lshl_add_u64 v[126:127], v[16:17], 0, v[8:9]
	v_lshl_add_u64 v[124:125], v[16:17], 0, v[14:15]
	v_add_co_u32_e32 v52, vcc, 0x9e00000, v126
	s_nop 1
	v_addc_co_u32_e32 v53, vcc, 0, v127, vcc
	v_add_co_u32_e32 v54, vcc, 0x9e16000, v126
	s_nop 1
	v_addc_co_u32_e32 v55, vcc, 0, v127, vcc
	v_lshl_add_u64 v[16:17], v[16:17], 0, s[8:9]
	global_load_dwordx4 v[128:131], v[124:125], off offset:-128
	global_load_dwordx4 v[132:135], v[124:125], off offset:-64
	global_load_dwordx4 v[136:139], v[124:125], off
	global_load_dwordx4 v[140:143], v[124:125], off offset:64
	global_load_dwordx4 v[144:147], v[52:53], off
	global_load_dwordx4 v[160:163], v[54:55], off
	global_load_dwordx4 v[148:151], v[52:53], off offset:64
	global_load_dwordx4 v[164:167], v[54:55], off offset:64
	global_load_dwordx4 v[152:155], v[52:53], off offset:128
	global_load_dwordx4 v[168:171], v[54:55], off offset:128
	global_load_dwordx4 v[156:159], v[52:53], off offset:192
	global_load_dwordx4 v[172:175], v[54:55], off offset:192
	s_waitcnt vmcnt(36)
	v_mfma_f32_16x16x32_bf16 v[4:7], v[176:179], v[196:199], v[4:7]
	v_mfma_f32_16x16x32_bf16 v[0:3], v[176:179], v[216:219], v[0:3]
	v_mfma_f32_16x16x32_bf16 v[4:7], v[180:183], v[204:207], v[4:7]
	v_mfma_f32_16x16x32_bf16 v[0:3], v[180:183], v[220:223], v[0:3]
	v_mfma_f32_16x16x32_bf16 v[4:7], v[184:187], v[208:211], v[4:7]
	v_mfma_f32_16x16x32_bf16 v[0:3], v[184:187], v[224:227], v[0:3]
	v_mfma_f32_16x16x32_bf16 v[4:7], v[192:195], v[212:215], v[4:7]
	v_mfma_f32_16x16x32_bf16 v[0:3], v[192:195], v[232:235], v[0:3]
	s_waitcnt vmcnt(24)
	v_mfma_f32_16x16x32_bf16 v[4:7], v[24:27], v[40:43], v[4:7]
	v_mfma_f32_16x16x32_bf16 v[0:3], v[24:27], v[48:51], v[0:3]
	v_mfma_f32_16x16x32_bf16 v[4:7], v[28:31], v[44:47], v[4:7]
	v_mfma_f32_16x16x32_bf16 v[0:3], v[28:31], v[64:67], v[0:3]
	v_mfma_f32_16x16x32_bf16 v[4:7], v[32:35], v[56:59], v[4:7]
	v_mfma_f32_16x16x32_bf16 v[0:3], v[32:35], v[68:71], v[0:3]
	v_mfma_f32_16x16x32_bf16 v[4:7], v[36:39], v[60:63], v[4:7]
	v_mfma_f32_16x16x32_bf16 v[0:3], v[36:39], v[72:75], v[0:3]
	s_waitcnt vmcnt(12)
	v_mfma_f32_16x16x32_bf16 v[4:7], v[76:79], v[92:95], v[4:7]
	v_mfma_f32_16x16x32_bf16 v[0:3], v[76:79], v[108:111], v[0:3]
	v_mfma_f32_16x16x32_bf16 v[4:7], v[80:83], v[96:99], v[4:7]
	v_mfma_f32_16x16x32_bf16 v[0:3], v[80:83], v[112:115], v[0:3]
	v_mfma_f32_16x16x32_bf16 v[4:7], v[84:87], v[100:103], v[4:7]
	v_mfma_f32_16x16x32_bf16 v[0:3], v[84:87], v[116:119], v[0:3]
	v_mfma_f32_16x16x32_bf16 v[4:7], v[88:91], v[104:107], v[4:7]
	v_mfma_f32_16x16x32_bf16 v[0:3], v[88:91], v[120:123], v[0:3]
	s_waitcnt vmcnt(0)
	v_mfma_f32_16x16x32_bf16 v[4:7], v[128:131], v[144:147], v[4:7]
	v_mfma_f32_16x16x32_bf16 v[0:3], v[128:131], v[160:163], v[0:3]
	v_mfma_f32_16x16x32_bf16 v[4:7], v[132:135], v[148:151], v[4:7]
	v_mfma_f32_16x16x32_bf16 v[0:3], v[132:135], v[164:167], v[0:3]
	v_mfma_f32_16x16x32_bf16 v[4:7], v[136:139], v[152:155], v[4:7]
	v_mfma_f32_16x16x32_bf16 v[0:3], v[136:139], v[168:171], v[0:3]
	v_mfma_f32_16x16x32_bf16 v[4:7], v[140:143], v[156:159], v[4:7]
	v_mfma_f32_16x16x32_bf16 v[0:3], v[140:143], v[172:175], v[0:3]
	s_nop 7
	s_andn2_b64 vcc, exec, s[2:3]
	s_cbranch_vccnz .LBB0_431
	s_nop 2
	ds_write_b128 v20, v[4:7] offset:32768
	s_nop 0
	ds_write_b128 v20, v[0:3] offset:32784

; template <bool PAIR, class F>
; __device__ __forceinline__ void skinny(const bf16_t* A, int lda, const bf16_t* Bt, int ldb, int K, int tile_lo, int tile_hi, int kmode, int bx, int G, int tid_, LAS unsigned char* lds, F f) {
;     ...
;         const int rbp = un & 3, cgrp = un >> 2, tile = tile_lo + cgrp / GPT, cgp = (cgrp % GPT) * 4 + cgl;
;         const int n0 = tile * 256 + cgp * 16, row0 = MP + rbp * 32 + fr;
;         const bf16_t* ap = A + (size_t)row0 * lda + (kmode ? 256 * (tile >> 1) : 0) + fq * 8;
;         const bf16_t* bp = Bt + (size_t)(n0 + fr) * ldb + fq * 8;
;         f32x4 a00 = (f32x4){0.f, 0.f, 0.f, 0.f}, a01 = a00, a10 = a00, a11 = a00;
;         for (int k0 = kbeg; k0 < kbeg + Kh; k0 += 128) {
; #pragma unroll
;             for (int kk = 0; kk < 128; kk += 32) {
;                 const bf16x8 x0 = *(const bf16x8*)(ap + k0 + kk), x1 = *(const bf16x8*)(ap + (size_t)16 * lda + k0 + kk), b = *(const bf16x8*)(bp + k0 + kk);
;                 a00 = __builtin_amdgcn_mfma_f32_16x16x32_bf16(b, x0, a00, 0, 0, 0); a01 = __builtin_amdgcn_mfma_f32_16x16x32_bf16(b, x1, a01, 0, 0, 0);
;                 if (PAIR) { const bf16x8 b2 = *(const bf16x8*)(bp + (size_t)128 * ldb + k0 + kk);
;                     a10 = __builtin_amdgcn_mfma_f32_16x16x32_bf16(b2, x0, a10, 0, 0, 0); a11 = __builtin_amdgcn_mfma_f32_16x16x32_bf16(b2, x1, a11, 0, 0, 0); }
;             }
.LBB0_1935:
	s_ashr_i32 s18, s23, 2
	s_lshr_b32 s19, s18, 30
	s_add_i32 s24, s18, s19
	s_and_b32 s19, s24, 0x3fffffc
	s_sub_i32 s18, s18, s19
	s_lshl_b32 s18, s18, 6
	s_or_b32 s19, s18, s17
	s_lshl_b32 s18, s23, 5
	s_and_b32 s18, s18, 0x60
	v_or_b32_e32 v22, s18, v18
	s_lshl_b32 s18, s24, 6
	s_and_b32 s18, s18, 0xffffff00
	s_add_i32 s24, s19, s18
	v_or_b32_e32 v23, 0x4000, v22
	v_or_b32_e32 v1, s24, v18
	v_mul_u32_u24_e32 v0, 0xb00, v23
	v_mad_i64_i32 v[14:15], s[24:25], v1, s22, v[12:13]
	v_lshlrev_b32_e32 v8, 1, v0
	v_mov_b64_e32 v[16:17], v[10:11]
	s_mov_b32 s24, s21
	v_mov_b32_e32 v4, v9
	v_mov_b32_e32 v5, v9
	v_mov_b32_e32 v6, v9
	v_mov_b32_e32 v7, v9
	v_mov_b32_e32 v0, v9
	v_mov_b32_e32 v1, v9
	v_mov_b32_e32 v2, v9
	v_mov_b32_e32 v3, v9
	v_lshl_add_u64 v[126:127], v[16:17], 0, v[8:9]
	v_lshl_add_u64 v[124:125], v[16:17], 0, v[14:15]
	v_add_co_u32_e32 v52, vcc, 0x9e00000, v126
	s_nop 1
	v_addc_co_u32_e32 v53, vcc, 0, v127, vcc
	v_add_co_u32_e32 v54, vcc, 0x9e16000, v126
	s_nop 1
	v_addc_co_u32_e32 v55, vcc, 0, v127, vcc
	v_lshl_add_u64 v[16:17], v[16:17], 0, s[12:13]
	global_load_dwordx4 v[24:27], v[124:125], off offset:-128
	global_load_dwordx4 v[28:31], v[124:125], off offset:-64
	global_load_dwordx4 v[32:35], v[124:125], off
	global_load_dwordx4 v[36:39], v[124:125], off offset:64
	global_load_dwordx4 v[40:43], v[52:53], off
	global_load_dwordx4 v[48:51], v[54:55], off
	global_load_dwordx4 v[44:47], v[52:53], off offset:64
	global_load_dwordx4 v[64:67], v[54:55], off offset:64
	global_load_dwordx4 v[56:59], v[52:53], off offset:128
	global_load_dwordx4 v[68:71], v[54:55], off offset:128
	global_load_dwordx4 v[60:63], v[52:53], off offset:192
	global_load_dwordx4 v[72:75], v[54:55], off offset:192
	v_lshl_add_u64 v[126:127], v[16:17], 0, v[8:9]
	v_lshl_add_u64 v[124:125], v[16:17], 0, v[14:15]
	v_add_co_u32_e32 v52, vcc, 0x9e00000, v126
	s_nop 1
	v_addc_co_u32_e32 v53, vcc, 0, v127, vcc
	v_add_co_u32_e32 v54, vcc, 0x9e16000, v126
	s_nop 1
	v_addc_co_u32_e32 v55, vcc, 0, v127, vcc
	v_lshl_add_u64 v[16:17], v[16:17], 0, s[12:13]
	global_load_dwordx4 v[76:79], v[124:125], off offset:-128
	global_load_dwordx4 v[80:83], v[124:125], off offset:-64
	global_load_dwordx4 v[84:87], v[124:125], off
	global_load_dwordx4 v[88:91], v[124:125], off offset:64
	global_load_dwordx4 v[92:95], v[52:53], off
	global_load_dwordx4 v[108:111], v[54:55], off
	global_load_dwordx4 v[96:99], v[52:53], off offset:64
	global_load_dwordx4 v[112:115], v[54:55], off offset:64
	global_load_dwordx4 v[100:103], v[52:53], off offset:128
	global_load_dwordx4 v[116:119], v[54:55], off offset:128
	global_load_dwordx4 v[104:107], v[52:53], off offset:192
	global_load_dwordx4 v[120:123], v[54:55], off offset:192
	v_lshl_add_u64 v[126:127], v[16:17], 0, v[8:9]
	v_lshl_add_u64 v[124:125], v[16:17], 0, v[14:15]
	v_add_co_u32_e32 v52, vcc, 0x9e00000, v126
	s_nop 1
	v_addc_co_u32_e32 v53, vcc, 0, v127, vcc
	v_add_co_u32_e32 v54, vcc, 0x9e16000, v126
	s_nop 1
	v_addc_co_u32_e32 v55, vcc, 0, v127, vcc
	v_lshl_add_u64 v[16:17], v[16:17], 0, s[12:13]
	global_load_dwordx4 v[128:131], v[124:125], off offset:-128
	global_load_dwordx4 v[132:135], v[124:125], off offset:-64
	global_load_dwordx4 v[136:139], v[124:125], off
	global_load_dwordx4 v[140:143], v[124:125], off offset:64
	global_load_dwordx4 v[144:147], v[52:53], off
	global_load_dwordx4 v[160:163], v[54:55], off
	global_load_dwordx4 v[148:151], v[52:53], off offset:64
	global_load_dwordx4 v[164:167], v[54:55], off offset:64
	global_load_dwordx4 v[152:155], v[52:53], off offset:128
	global_load_dwordx4 v[168:171], v[54:55], off offset:128
	global_load_dwordx4 v[156:159], v[52:53], off offset:192
	global_load_dwordx4 v[172:175], v[54:55], off offset:192
	v_lshl_add_u64 v[126:127], v[16:17], 0, v[8:9]
	v_lshl_add_u64 v[124:125], v[16:17], 0, v[14:15]
	v_add_co_u32_e32 v52, vcc, 0x9e00000, v126
	s_nop 1
	v_addc_co_u32_e32 v53, vcc, 0, v127, vcc
	v_add_co_u32_e32 v54, vcc, 0x9e16000, v126
	s_nop 1
	v_addc_co_u32_e32 v55, vcc, 0, v127, vcc
	v_lshl_add_u64 v[16:17], v[16:17], 0, s[12:13]
	global_load_dwordx4 v[176:179], v[124:125], off offset:-128
	global_load_dwordx4 v[180:183], v[124:125], off offset:-64
	global_load_dwordx4 v[184:187], v[124:125], off
	global_load_dwordx4 v[192:195], v[124:125], off offset:64
	global_load_dwordx4 v[196:199], v[52:53], off
	global_load_dwordx4 v[216:219], v[54:55], off
	global_load_dwordx4 v[204:207], v[52:53], off offset:64
	global_load_dwordx4 v[220:223], v[54:55], off offset:64
	global_load_dwordx4 v[208:211], v[52:53], off offset:128
	global_load_dwordx4 v[224:227], v[54:55], off offset:128
	global_load_dwordx4 v[212:215], v[52:53], off offset:192
	global_load_dwordx4 v[232:235], v[54:55], off offset:192
	s_waitcnt vmcnt(36)
	v_mfma_f32_16x16x32_bf16 v[4:7], v[24:27], v[40:43], v[4:7]
	v_mfma_f32_16x16x32_bf16 v[0:3], v[24:27], v[48:51], v[0:3]
	v_mfma_f32_16x16x32_bf16 v[4:7], v[28:31], v[44:47], v[4:7]
	v_mfma_f32_16x16x32_bf16 v[0:3], v[28:31], v[64:67], v[0:3]
	v_mfma_f32_16x16x32_bf16 v[4:7], v[32:35], v[56:59], v[4:7]
	v_mfma_f32_16x16x32_bf16 v[0:3], v[32:35], v[68:71], v[0:3]
	v_mfma_f32_16x16x32_bf16 v[4:7], v[36:39], v[60:63], v[4:7]
	v_mfma_f32_16x16x32_bf16 v[0:3], v[36:39], v[72:75], v[0:3]
	v_lshl_add_u64 v[126:127], v[16:17], 0, v[8:9]
	v_lshl_add_u64 v[124:125], v[16:17], 0, v[14:15]
	v_add_co_u32_e32 v52, vcc, 0x9e00000, v126
	s_nop 1
	v_addc_co_u32_e32 v53, vcc, 0, v127, vcc
	v_add_co_u32_e32 v54, vcc, 0x9e16000, v126
	s_nop 1
	v_addc_co_u32_e32 v55, vcc, 0, v127, vcc
	v_lshl_add_u64 v[16:17], v[16:17], 0, s[12:13]
	global_load_dwordx4 v[24:27], v[124:125], off offset:-128
	global_load_dwordx4 v[28:31], v[124:125], off offset:-64
	global_load_dwordx4 v[32:35], v[124:125], off
	global_load_dwordx4 v[36:39], v[124:125], off offset:64
	global_load_dwordx4 v[40:43], v[52:53], off
	global_load_dwordx4 v[48:51], v[54:55], off
	global_load_dwordx4 v[44:47], v[52:53], off offset:64
	global_load_dwordx4 v[64:67], v[54:55], off offset:64
	global_load_dwordx4 v[56:59], v[52:53], off offset:128
	global_load_dwordx4 v[68:71], v[54:55], off offset:128
	global_load_dwordx4 v[60:63], v[52:53], off offset:192
	global_load_dwordx4 v[72:75], v[54:55], off offset:192
	s_waitcnt vmcnt(36)
; template <bool PAIR, class F>
; __device__ __forceinline__ void skinny(const bf16_t* A, int lda, const bf16_t* Bt, int ldb, int K, int tile_lo, int tile_hi, int kmode, int bx, int G, int tid_, LAS unsigned char* lds, F f) {
;     ...
;         for (int k0 = kbeg; k0 < kbeg + Kh; k0 += 128) {
; #pragma unroll
;             for (int kk = 0; kk < 128; kk += 32) {
;                 const bf16x8 x0 = *(const bf16x8*)(ap + k0 + kk), x1 = *(const bf16x8*)(ap + (size_t)16 * lda + k0 + kk), b = *(const bf16x8*)(bp + k0 + kk);
;                 a00 = __builtin_amdgcn_mfma_f32_16x16x32_bf16(b, x0, a00, 0, 0, 0); a01 = __builtin_amdgcn_mfma_f32_16x16x32_bf16(b, x1, a01, 0, 0, 0);
;                 if (PAIR) { const bf16x8 b2 = *(const bf16x8*)(bp + (size_t)128 * ldb + k0 + kk);
;                     a10 = __builtin_amdgcn_mfma_f32_16x16x32_bf16(b2, x0, a10, 0, 0, 0); a11 = __builtin_amdgcn_mfma_f32_16x16x32_bf16(b2, x1, a11, 0, 0, 0); }
;             }
	v_mfma_f32_16x16x32_bf16 v[4:7], v[76:79], v[92:95], v[4:7]
	v_mfma_f32_16x16x32_bf16 v[0:3], v[76:79], v[108:111], v[0:3]
	v_mfma_f32_16x16x32_bf16 v[4:7], v[80:83], v[96:99], v[4:7]
	v_mfma_f32_16x16x32_bf16 v[0:3], v[80:83], v[112:115], v[0:3]
	v_mfma_f32_16x16x32_bf16 v[4:7], v[84:87], v[100:103], v[4:7]
	v_mfma_f32_16x16x32_bf16 v[0:3], v[84:87], v[116:119], v[0:3]
	v_mfma_f32_16x16x32_bf16 v[4:7], v[88:91], v[104:107], v[4:7]
	v_mfma_f32_16x16x32_bf16 v[0:3], v[88:91], v[120:123], v[0:3]
	v_lshl_add_u64 v[126:127], v[16:17], 0, v[8:9]
	v_lshl_add_u64 v[124:125], v[16:17], 0, v[14:15]
	v_add_co_u32_e32 v52, vcc, 0x9e00000, v126
	s_nop 1
	v_addc_co_u32_e32 v53, vcc, 0, v127, vcc
	v_add_co_u32_e32 v54, vcc, 0x9e16000, v126
	s_nop 1
	v_addc_co_u32_e32 v55, vcc, 0, v127, vcc
	v_lshl_add_u64 v[16:17], v[16:17], 0, s[12:13]
	global_load_dwordx4 v[76:79], v[124:125], off offset:-128
	global_load_dwordx4 v[80:83], v[124:125], off offset:-64
	global_load_dwordx4 v[84:87], v[124:125], off
	global_load_dwordx4 v[88:91], v[124:125], off offset:64
	global_load_dwordx4 v[92:95], v[52:53], off
	global_load_dwordx4 v[108:111], v[54:55], off
	global_load_dwordx4 v[96:99], v[52:53], off offset:64
	global_load_dwordx4 v[112:115], v[54:55], off offset:64
	global_load_dwordx4 v[100:103], v[52:53], off offset:128
	global_load_dwordx4 v[116:119], v[54:55], off offset:128
	global_load_dwordx4 v[104:107], v[52:53], off offset:192
	global_load_dwordx4 v[120:123], v[54:55], off offset:192
	s_waitcnt vmcnt(36)
	v_mfma_f32_16x16x32_bf16 v[4:7], v[128:131], v[144:147], v[4:7]
	v_mfma_f32_16x16x32_bf16 v[0:3], v[128:131], v[160:163], v[0:3]
	v_mfma_f32_16x16x32_bf16 v[4:7], v[132:135], v[148:151], v[4:7]
	v_mfma_f32_16x16x32_bf16 v[0:3], v[132:135], v[164:167], v[0:3]
	v_mfma_f32_16x16x32_bf16 v[4:7], v[136:139], v[152:155], v[4:7]
	v_mfma_f32_16x16x32_bf16 v[0:3], v[136:139], v[168:171], v[0:3]
	v_mfma_f32_16x16x32_bf16 v[4:7], v[140:143], v[156:159], v[4:7]
	v_mfma_f32_16x16x32_bf16 v[0:3], v[140:143], v[172:175], v[0:3]
	v_lshl_add_u64 v[126:127], v[16:17], 0, v[8:9]
	v_lshl_add_u64 v[124:125], v[16:17], 0, v[14:15]
	v_add_co_u32_e32 v52, vcc, 0x9e00000, v126
	s_nop 1
	v_addc_co_u32_e32 v53, vcc, 0, v127, vcc
	v_add_co_u32_e32 v54, vcc, 0x9e16000, v126
	s_nop 1
	v_addc_co_u32_e32 v55, vcc, 0, v127, vcc
	v_lshl_add_u64 v[16:17], v[16:17], 0, s[12:13]
	global_load_dwordx4 v[128:131], v[124:125], off offset:-128
	global_load_dwordx4 v[132:135], v[124:125], off offset:-64
	global_load_dwordx4 v[136:139], v[124:125], off
	global_load_dwordx4 v[140:143], v[124:125], off offset:64
	global_load_dwordx4 v[144:147], v[52:53], off
	global_load_dwordx4 v[160:163], v[54:55], off
	global_load_dwordx4 v[148:151], v[52:53], off offset:64
	global_load_dwordx4 v[164:167], v[54:55], off offset:64
	global_load_dwordx4 v[152:155], v[52:53], off offset:128
	global_load_dwordx4 v[168:171], v[54:55], off offset:128
	global_load_dwordx4 v[156:159], v[52:53], off offset:192
	global_load_dwordx4 v[172:175], v[54:55], off offset:192
	s_waitcnt vmcnt(36)
	v_mfma_f32_16x16x32_bf16 v[4:7], v[176:179], v[196:199], v[4:7]
	v_mfma_f32_16x16x32_bf16 v[0:3], v[176:179], v[216:219], v[0:3]
	v_mfma_f32_16x16x32_bf16 v[4:7], v[180:183], v[204:207], v[4:7]
	v_mfma_f32_16x16x32_bf16 v[0:3], v[180:183], v[220:223], v[0:3]
	v_mfma_f32_16x16x32_bf16 v[4:7], v[184:187], v[208:211], v[4:7]
	v_mfma_f32_16x16x32_bf16 v[0:3], v[184:187], v[224:227], v[0:3]
	v_mfma_f32_16x16x32_bf16 v[4:7], v[192:195], v[212:215], v[4:7]
	v_mfma_f32_16x16x32_bf16 v[0:3], v[192:195], v[232:235], v[0:3]
	v_lshl_add_u64 v[126:127], v[16:17], 0, v[8:9]
	v_lshl_add_u64 v[124:125], v[16:17], 0, v[14:15]
	v_add_co_u32_e32 v52, vcc, 0x9e00000, v126
	s_nop 1
	v_addc_co_u32_e32 v53, vcc, 0, v127, vcc
	v_add_co_u32_e32 v54, vcc, 0x9e16000, v126
	s_nop 1
	v_addc_co_u32_e32 v55, vcc, 0, v127, vcc
	v_lshl_add_u64 v[16:17], v[16:17], 0, s[12:13]
	global_load_dwordx4 v[176:179], v[124:125], off offset:-128
	global_load_dwordx4 v[180:183], v[124:125], off offset:-64
	global_load_dwordx4 v[184:187], v[124:125], off
	global_load_dwordx4 v[192:195], v[124:125], off offset:64
	global_load_dwordx4 v[196:199], v[52:53], off
	global_load_dwordx4 v[216:219], v[54:55], off
	global_load_dwordx4 v[204:207], v[52:53], off offset:64
	global_load_dwordx4 v[220:223], v[54:55], off offset:64
	global_load_dwordx4 v[208:211], v[52:53], off offset:128
	global_load_dwordx4 v[224:227], v[54:55], off offset:128
	global_load_dwordx4 v[212:215], v[52:53], off offset:192
	global_load_dwordx4 v[232:235], v[54:55], off offset:192
	s_waitcnt vmcnt(36)
	v_mfma_f32_16x16x32_bf16 v[4:7], v[24:27], v[40:43], v[4:7]
	v_mfma_f32_16x16x32_bf16 v[0:3], v[24:27], v[48:51], v[0:3]
	v_mfma_f32_16x16x32_bf16 v[4:7], v[28:31], v[44:47], v[4:7]
	v_mfma_f32_16x16x32_bf16 v[0:3], v[28:31], v[64:67], v[0:3]
	v_mfma_f32_16x16x32_bf16 v[4:7], v[32:35], v[56:59], v[4:7]
	v_mfma_f32_16x16x32_bf16 v[0:3], v[32:35], v[68:71], v[0:3]
	v_mfma_f32_16x16x32_bf16 v[4:7], v[36:39], v[60:63], v[4:7]
	v_mfma_f32_16x16x32_bf16 v[0:3], v[36:39], v[72:75], v[0:3]
	v_lshl_add_u64 v[126:127], v[16:17], 0, v[8:9]
	v_lshl_add_u64 v[124:125], v[16:17], 0, v[14:15]
	v_add_co_u32_e32 v52, vcc, 0x9e00000, v126
	s_nop 1
	v_addc_co_u32_e32 v53, vcc, 0, v127, vcc
	v_add_co_u32_e32 v54, vcc, 0x9e16000, v126
	s_nop 1
	v_addc_co_u32_e32 v55, vcc, 0, v127, vcc
	v_lshl_add_u64 v[16:17], v[16:17], 0, s[12:13]
	global_load_dwordx4 v[24:27], v[124:125], off offset:-128
	global_load_dwordx4 v[28:31], v[124:125], off offset:-64
	global_load_dwordx4 v[32:35], v[124:125], off
	global_load_dwordx4 v[36:39], v[124:125], off offset:64
	global_load_dwordx4 v[40:43], v[52:53], off
	global_load_dwordx4 v[48:51], v[54:55], off
	global_load_dwordx4 v[44:47], v[52:53], off offset:64
	global_load_dwordx4 v[64:67], v[54:55], off offset:64
	global_load_dwordx4 v[56:59], v[52:53], off offset:128
	global_load_dwordx4 v[68:71], v[54:55], off offset:128
	global_load_dwordx4 v[60:63], v[52:53], off offset:192
	global_load_dwordx4 v[72:75], v[54:55], off offset:192
	s_waitcnt vmcnt(36)
; template <bool PAIR, class F>
; __device__ __forceinline__ void skinny(const bf16_t* A, int lda, const bf16_t* Bt, int ldb, int K, int tile_lo, int tile_hi, int kmode, int bx, int G, int tid_, LAS unsigned char* lds, F f) {
;     ...
;         for (int k0 = kbeg; k0 < kbeg + Kh; k0 += 128) {
; #pragma unroll
;             for (int kk = 0; kk < 128; kk += 32) {
;                 const bf16x8 x0 = *(const bf16x8*)(ap + k0 + kk), x1 = *(const bf16x8*)(ap + (size_t)16 * lda + k0 + kk), b = *(const bf16x8*)(bp + k0 + kk);
;                 a00 = __builtin_amdgcn_mfma_f32_16x16x32_bf16(b, x0, a00, 0, 0, 0); a01 = __builtin_amdgcn_mfma_f32_16x16x32_bf16(b, x1, a01, 0, 0, 0);
;                 if (PAIR) { const bf16x8 b2 = *(const bf16x8*)(bp + (size_t)128 * ldb + k0 + kk);
;                     a10 = __builtin_amdgcn_mfma_f32_16x16x32_bf16(b2, x0, a10, 0, 0, 0); a11 = __builtin_amdgcn_mfma_f32_16x16x32_bf16(b2, x1, a11, 0, 0, 0); }
;             }
;         }
;         if (kh == 1) { X[0] = a00; X[1] = a01; if (PAIR) { X[2] = a10; X[3] = a11; } }
	v_mfma_f32_16x16x32_bf16 v[4:7], v[76:79], v[92:95], v[4:7]
	v_mfma_f32_16x16x32_bf16 v[0:3], v[76:79], v[108:111], v[0:3]
	v_mfma_f32_16x16x32_bf16 v[4:7], v[80:83], v[96:99], v[4:7]
	v_mfma_f32_16x16x32_bf16 v[0:3], v[80:83], v[112:115], v[0:3]
	v_mfma_f32_16x16x32_bf16 v[4:7], v[84:87], v[100:103], v[4:7]
	v_mfma_f32_16x16x32_bf16 v[0:3], v[84:87], v[116:119], v[0:3]
	v_mfma_f32_16x16x32_bf16 v[4:7], v[88:91], v[104:107], v[4:7]
	v_mfma_f32_16x16x32_bf16 v[0:3], v[88:91], v[120:123], v[0:3]
	v_lshl_add_u64 v[126:127], v[16:17], 0, v[8:9]
	v_lshl_add_u64 v[124:125], v[16:17], 0, v[14:15]
	v_add_co_u32_e32 v52, vcc, 0x9e00000, v126
	s_nop 1
	v_addc_co_u32_e32 v53, vcc, 0, v127, vcc
	v_add_co_u32_e32 v54, vcc, 0x9e16000, v126
	s_nop 1
	v_addc_co_u32_e32 v55, vcc, 0, v127, vcc
	v_lshl_add_u64 v[16:17], v[16:17], 0, s[12:13]
	global_load_dwordx4 v[76:79], v[124:125], off offset:-128
	global_load_dwordx4 v[80:83], v[124:125], off offset:-64
	global_load_dwordx4 v[84:87], v[124:125], off
	global_load_dwordx4 v[88:91], v[124:125], off offset:64
	global_load_dwordx4 v[92:95], v[52:53], off
	global_load_dwordx4 v[108:111], v[54:55], off
	global_load_dwordx4 v[96:99], v[52:53], off offset:64
	global_load_dwordx4 v[112:115], v[54:55], off offset:64
	global_load_dwordx4 v[100:103], v[52:53], off offset:128
	global_load_dwordx4 v[116:119], v[54:55], off offset:128
	global_load_dwordx4 v[104:107], v[52:53], off offset:192
	global_load_dwordx4 v[120:123], v[54:55], off offset:192
	s_waitcnt vmcnt(36)
	v_mfma_f32_16x16x32_bf16 v[4:7], v[128:131], v[144:147], v[4:7]
	v_mfma_f32_16x16x32_bf16 v[0:3], v[128:131], v[160:163], v[0:3]
	v_mfma_f32_16x16x32_bf16 v[4:7], v[132:135], v[148:151], v[4:7]
	v_mfma_f32_16x16x32_bf16 v[0:3], v[132:135], v[164:167], v[0:3]
	v_mfma_f32_16x16x32_bf16 v[4:7], v[136:139], v[152:155], v[4:7]
	v_mfma_f32_16x16x32_bf16 v[0:3], v[136:139], v[168:171], v[0:3]
	v_mfma_f32_16x16x32_bf16 v[4:7], v[140:143], v[156:159], v[4:7]
	v_mfma_f32_16x16x32_bf16 v[0:3], v[140:143], v[172:175], v[0:3]
	v_lshl_add_u64 v[126:127], v[16:17], 0, v[8:9]
	v_lshl_add_u64 v[124:125], v[16:17], 0, v[14:15]
	v_add_co_u32_e32 v52, vcc, 0x9e00000, v126
	s_nop 1
	v_addc_co_u32_e32 v53, vcc, 0, v127, vcc
	v_add_co_u32_e32 v54, vcc, 0x9e16000, v126
	s_nop 1
	v_addc_co_u32_e32 v55, vcc, 0, v127, vcc
	v_lshl_add_u64 v[16:17], v[16:17], 0, s[12:13]
	global_load_dwordx4 v[128:131], v[124:125], off offset:-128
	global_load_dwordx4 v[132:135], v[124:125], off offset:-64
	global_load_dwordx4 v[136:139], v[124:125], off
	global_load_dwordx4 v[140:143], v[124:125], off offset:64
	global_load_dwordx4 v[144:147], v[52:53], off
	global_load_dwordx4 v[160:163], v[54:55], off
	global_load_dwordx4 v[148:151], v[52:53], off offset:64
	global_load_dwordx4 v[164:167], v[54:55], off offset:64
	global_load_dwordx4 v[152:155], v[52:53], off offset:128
	global_load_dwordx4 v[168:171], v[54:55], off offset:128
	global_load_dwordx4 v[156:159], v[52:53], off offset:192
	global_load_dwordx4 v[172:175], v[54:55], off offset:192
	s_waitcnt vmcnt(36)
	v_mfma_f32_16x16x32_bf16 v[4:7], v[176:179], v[196:199], v[4:7]
	v_mfma_f32_16x16x32_bf16 v[0:3], v[176:179], v[216:219], v[0:3]
	v_mfma_f32_16x16x32_bf16 v[4:7], v[180:183], v[204:207], v[4:7]
	v_mfma_f32_16x16x32_bf16 v[0:3], v[180:183], v[220:223], v[0:3]
	v_mfma_f32_16x16x32_bf16 v[4:7], v[184:187], v[208:211], v[4:7]
	v_mfma_f32_16x16x32_bf16 v[0:3], v[184:187], v[224:227], v[0:3]
	v_mfma_f32_16x16x32_bf16 v[4:7], v[192:195], v[212:215], v[4:7]
	v_mfma_f32_16x16x32_bf16 v[0:3], v[192:195], v[232:235], v[0:3]
	s_waitcnt vmcnt(24)
	v_mfma_f32_16x16x32_bf16 v[4:7], v[24:27], v[40:43], v[4:7]
	v_mfma_f32_16x16x32_bf16 v[0:3], v[24:27], v[48:51], v[0:3]
	v_mfma_f32_16x16x32_bf16 v[4:7], v[28:31], v[44:47], v[4:7]
	v_mfma_f32_16x16x32_bf16 v[0:3], v[28:31], v[64:67], v[0:3]
	v_mfma_f32_16x16x32_bf16 v[4:7], v[32:35], v[56:59], v[4:7]
	v_mfma_f32_16x16x32_bf16 v[0:3], v[32:35], v[68:71], v[0:3]
	v_mfma_f32_16x16x32_bf16 v[4:7], v[36:39], v[60:63], v[4:7]
	v_mfma_f32_16x16x32_bf16 v[0:3], v[36:39], v[72:75], v[0:3]
	s_waitcnt vmcnt(12)
	v_mfma_f32_16x16x32_bf16 v[4:7], v[76:79], v[92:95], v[4:7]
	v_mfma_f32_16x16x32_bf16 v[0:3], v[76:79], v[108:111], v[0:3]
	v_mfma_f32_16x16x32_bf16 v[4:7], v[80:83], v[96:99], v[4:7]
	v_mfma_f32_16x16x32_bf16 v[0:3], v[80:83], v[112:115], v[0:3]
	v_mfma_f32_16x16x32_bf16 v[4:7], v[84:87], v[100:103], v[4:7]
	v_mfma_f32_16x16x32_bf16 v[0:3], v[84:87], v[116:119], v[0:3]
	v_mfma_f32_16x16x32_bf16 v[4:7], v[88:91], v[104:107], v[4:7]
	v_mfma_f32_16x16x32_bf16 v[0:3], v[88:91], v[120:123], v[0:3]
	s_waitcnt vmcnt(0)
	v_mfma_f32_16x16x32_bf16 v[4:7], v[128:131], v[144:147], v[4:7]
	v_mfma_f32_16x16x32_bf16 v[0:3], v[128:131], v[160:163], v[0:3]
	v_mfma_f32_16x16x32_bf16 v[4:7], v[132:135], v[148:151], v[4:7]
	v_mfma_f32_16x16x32_bf16 v[0:3], v[132:135], v[164:167], v[0:3]
	v_mfma_f32_16x16x32_bf16 v[4:7], v[136:139], v[152:155], v[4:7]
	v_mfma_f32_16x16x32_bf16 v[0:3], v[136:139], v[168:171], v[0:3]
	v_mfma_f32_16x16x32_bf16 v[4:7], v[140:143], v[156:159], v[4:7]
	v_mfma_f32_16x16x32_bf16 v[0:3], v[140:143], v[172:175], v[0:3]
	s_nop 7
	s_andn2_b64 vcc, exec, s[2:3]
	s_cbranch_vccnz .LBB0_1939
	s_nop 3
	ds_write_b128 v20, v[4:7] offset:32768
	ds_write_b128 v20, v[0:3] offset:32784
